# B2 + split phase: cached-context row loads issued without waiting, converted and stored at phase exit (prologue de-serialisation)
# baseline (speedup 1.0000x reference)
.LBB0_175:
	s_and_b64 vcc, exec, s[0:1]
	s_cbranch_vccz .LBB0_215
	s_cmp_gt_i32 s98, 0
	s_mov_b64 s[0:1], -1
	s_cbranch_scc0 .LBB0_217
	s_mov_b32 s100, 0
	v_readlane_b32 s0, v252, 13
	v_mbcnt_lo_u32_b32 v24, -1, 0
	v_mbcnt_hi_u32_b32 v24, -1, v24
	v_readlane_b32 s1, v252, 14
	v_lshlrev_b32_e32 v26, 2, v24
	s_mov_b64 s[66:67], s[22:23]
	s_waitcnt lgkmcnt(0)
	s_lshl_b32 s9, s79, 3
	v_ashrrev_i32_e32 v27, 31, v26
	s_andn2_b64 vcc, exec, s[0:1]
	v_ashrrev_i32_e32 v25, 31, v24
	s_cbranch_vccnz .LBB0_180
	v_readlane_b32 s0, v252, 5
	v_readlane_b32 s1, v252, 6
	v_lshl_add_u64 v[4:5], v[26:27], 2, s[48:49]
	v_lshl_add_u64 v[6:7], v[24:25], 2, s[50:51]
	v_lshl_add_u64 v[0:1], v[26:27], 1, s[0:1]
	v_readlane_b32 s0, v251, 35
	v_readlane_b32 s1, v251, 36
	s_nop 1
	v_lshl_add_u64 v[2:3], v[24:25], 1, s[0:1]
	v_readlane_b32 s0, v255, 33
	v_readlane_b32 s1, v255, 34
	s_cmpk_lt_u32 s9, 0x800
	s_cbranch_scc1 .LBB0_179
	s_ashr_i32 s5, s0, 7
	s_and_b32 s5, s5, -4
	s_add_i32 s6, s5, s8
	s_ashr_i32 s7, s6, 31
	s_and_b32 s1, s0, 0x1ff
	s_lshl_b64 s[6:7], s[6:7], 9
	s_or_b32 s6, s6, s1
	s_add_i32 s4, s0, 0x3000
	s_lshl_b64 s[10:11], s[6:7], 10
	v_lshl_add_u64 v[140:141], v[4:5], 0, s[10:11]
	s_lshl_b64 s[6:7], s[6:7], 8
	s_ashr_i32 s5, s4, 31
	global_load_dwordx4 v[130:133], v[140:141], off
	v_lshl_add_u64 v[142:143], v[6:7], 0, s[6:7]
	s_lshl_b64 s[6:7], s[4:5], 9
	global_load_dword v134, v[142:143], off
	v_lshl_add_u64 v[136:137], v[0:1], 0, s[6:7]
	s_lshl_b64 s[4:5], s[4:5], 7
	v_lshl_add_u64 v[138:139], v[2:3], 0, s[4:5]
	s_mov_b32 s100, 1
	s_branch .LBB0_180

.LBB0_216:
	s_cmp_lg_u32 s100, 1
	s_cbranch_scc1 .Lsp_nodefer
	v_cvt_pk_bf16_f32 v130, v130, v131
	v_cvt_pk_bf16_f32 v131, v132, v133
	v_cvt_pk_bf16_f32 v132, v134, v81
	s_nop 0
	global_store_dwordx2 v[136:137], v[130:131], off
	global_store_short v[138:139], v132, off
	s_mov_b32 s100, 0
